# first grid barrier: the 16 per-XCD arrival-counter loads of the census issued back to back with one wait (were 16 dependent sc1 round trips on the first barrier's critical path)
# speedup vs baseline: 1.0054x; 1.0054x over previous
.LBB0_695:
	s_mov_b64 s[28:29], -1
	s_mov_b64 s[30:31], -1
	s_waitcnt lgkmcnt(0)
	global_load_dword v0, v1, s[22:23] sc1
	v_readlane_b32 s14, v254, 6
	v_readlane_b32 s15, v254, 7
	s_nop 4
	global_load_dword v2, v1, s[14:15] sc1
	v_readlane_b32 s14, v254, 8
	v_readlane_b32 s15, v254, 9
	s_nop 4
	global_load_dword v3, v1, s[14:15] sc1
	v_readlane_b32 s14, v254, 10
	v_readlane_b32 s15, v254, 11
	s_nop 4
	global_load_dword v4, v1, s[14:15] sc1
	v_readlane_b32 s14, v254, 12
	v_readlane_b32 s15, v254, 13
	s_nop 4
	global_load_dword v5, v1, s[14:15] sc1
	v_readlane_b32 s14, v254, 14
	v_readlane_b32 s15, v254, 15
	s_nop 4
	global_load_dword v6, v1, s[14:15] sc1
	v_readlane_b32 s14, v254, 16
	v_readlane_b32 s15, v254, 17
	s_nop 4
	global_load_dword v7, v1, s[14:15] sc1
	v_readlane_b32 s14, v254, 18
	v_readlane_b32 s15, v254, 19
	s_nop 4
	global_load_dword v8, v1, s[14:15] sc1
	v_readlane_b32 s14, v254, 20
	v_readlane_b32 s15, v254, 21
	s_nop 4
	global_load_dword v9, v1, s[14:15] sc1
	v_readlane_b32 s14, v254, 22
	v_readlane_b32 s15, v254, 23
	s_nop 4
	global_load_dword v10, v1, s[14:15] sc1
	v_readlane_b32 s14, v254, 24
	v_readlane_b32 s15, v254, 25
	s_nop 4
	global_load_dword v11, v1, s[14:15] sc1
	v_readlane_b32 s14, v254, 26
	v_readlane_b32 s15, v254, 27
	s_nop 4
	global_load_dword v12, v1, s[14:15] sc1
	v_readlane_b32 s14, v254, 28
	v_readlane_b32 s15, v254, 29
	s_nop 4
	global_load_dword v13, v1, s[14:15] sc1
	v_readlane_b32 s14, v254, 30
	v_readlane_b32 s15, v254, 31
	s_nop 4
	global_load_dword v14, v1, s[14:15] sc1
	v_readlane_b32 s14, v254, 32
	v_readlane_b32 s15, v254, 33
	s_nop 4
	global_load_dword v15, v1, s[14:15] sc1
	v_readlane_b32 s14, v254, 34
	v_readlane_b32 s15, v254, 35
	s_nop 4
	global_load_dword v16, v1, s[14:15] sc1
	s_waitcnt vmcnt(0)
	v_add_u32_e32 v17, v2, v0
	v_add_u32_e32 v17, v17, v3
	v_add_u32_e32 v17, v17, v4
	v_add_u32_e32 v17, v17, v5
	v_add_u32_e32 v17, v17, v6
	v_add_u32_e32 v17, v17, v7
	v_add_u32_e32 v17, v17, v8
	v_add_u32_e32 v17, v17, v9
	v_add_u32_e32 v17, v17, v10
	v_add_u32_e32 v17, v17, v11
	v_add_u32_e32 v17, v17, v12
	v_add_u32_e32 v17, v17, v13
	v_add_u32_e32 v17, v17, v14
	v_add_u32_e32 v17, v17, v15
	v_add_u32_e32 v17, v17, v16
	v_cmp_eq_u32_e32 vcc, s12, v17
	s_cbranch_vccnz .LBB0_694
	s_and_b32 s6, s2, 0xff
	s_cmp_eq_u32 s6, 0
	s_mov_b64 s[36:37], -1
	s_sleep 1
	s_cbranch_scc0 .LBB0_699
	v_readlane_b32 s14, v254, 4
	v_readlane_b32 s15, v254, 5
	s_nop 4
	global_load_dword v17, v1, s[14:15] sc1
	s_waitcnt vmcnt(0)
	v_cmp_eq_u32_e32 vcc, 0, v17
	s_cbranch_vccnz .LBB0_701
	s_mov_b64 s[36:37], 0
